# 4096 weight items per recurrence phase moved to the streamer WGs, with grid-size guards (the overlap is used only on a 256-workgroup grid; otherwise the prologue converts everything as before)
# baseline (speedup 1.0000x reference)
; __device__ __forceinline__ int tidx() { int t = threadIdx.x; asm volatile("" : "+v"(t)); return t; }
; #define LAS __attribute__((address_space(3)))
; __device__ __forceinline__ void phase_prologue(const P& p, unsigned char* ws, LAS unsigned char* lds, int wg, int nwg) {
;     const int tid = tidx(), lane = tid & 63, wave = tid >> 6;
;     LAS float* scr = (LAS float*)(lds + wave * 16384);
;     const int gw = wg * NWAVES + wave, NGW = nwg * NWAVES;
;     constexpr int I_IN = (D / 64) * (NZ / 32), I_UH = (HW / 64) * (D / 32), I_UG = I_UH, I_OUT = (D / 64) * (D / 32), I_F1 = (D / 64) * (DFF / 32), I_F2 = (DFF / 64) * (D / 32), I_PL = (PLE / 64) * (D / 32), I_PG = I_OUT;
;     constexpr int I_LAYER = I_IN + I_UH + I_UG + I_OUT + I_F1 + I_F2 + I_PL + I_PG;
;     for (int it = gw; it < DEPTH * I_LAYER; it += NGW) {
.Lcv_entry:
	v_readlane_b32 s18, v249, 4
	s_mov_b32 s26, s2
	s_mov_b32 s24, s95
	v_readlane_b32 s19, v249, 5
	v_readlane_b32 s0, v250, 0
	s_bitcmp1_b32 s0, 0
	s_cbranch_scc1 .Lcv_conv
	s_cmp_lg_u32 s0, 0
	s_cbranch_scc1 .Lcv_m0
	s_cmpk_eq_u32 s95, 0x100
	s_cbranch_scc1 .Lcv_m0
	s_mov_b32 s0, 0x21c00
	v_writelane_b32 v250, s0, 2
	s_mov_b32 s0, 0x21bff
	v_writelane_b32 v250, s0, 3
	s_branch .Lcv_m0
.Lcv_conv:
	v_readlane_b32 s26, v250, 4
	s_movk_i32 s24, 0x80

; #define LAS __attribute__((address_space(3)))
; __device__ __forceinline__ void phase_prologue(const P& p, unsigned char* ws, LAS unsigned char* lds, int wg, int nwg) {
;     ...
;     for (int it = gw; it < DEPTH * I_LAYER; it += NGW) {
;         const int l = it / I_LAYER; int r = it % I_LAYER;
; __device__ __forceinline__ void phase_rec(const P& p, unsigned char* ws, int l, LAS unsigned char* lds, int wg, int nwg) {
;     int lrank = wg, nloop = nwg, srank = wg, nstr = nwg;
;     const bool split = nwg >= 16;
;     if (split) { const int grp = wg >> 3, ngrp = (nwg + 7) >> 3, nlg = (ngrp + 1) >> 1;
;         const int full_l = nlg * 8 - ((ngrp & 1) ? (ngrp * 8 - nwg) : 0), full_s = nwg - full_l;
;         nloop = full_l; nstr = full_s; lrank = (grp >> 1) * 8 + (wg & 7); srank = (grp >> 1) * 8 + (wg & 7);
;         if (grp & 1) lrank = 1 << 30; else srank = 1 << 30; }
;     for (int rl = 0; rl < REP_LOOP; ++rl) for (int tk = lrank; tk < 128; tk += nloop) rec_loop_task(p, ws, l, lds, tk);
.LBB0_1145:
	v_readlane_b32 s0, v248, 27
	s_cmp_gt_u32 s0, 2
	s_cbranch_scc1 .Lcv_skip
	v_readlane_b32 s22, v248, 20
	s_cmpk_lg_u32 s22, 0x100
	s_cbranch_scc1 .Lcv_skip
	v_readlane_b32 s1, v248, 19
	s_bitcmp1_b32 s1, 3
	s_cbranch_scc0 .Lcv_skip
	s_waitcnt lgkmcnt(0)
	s_barrier
	v_writelane_b32 v251, s3, 0
	v_writelane_b32 v251, s4, 1
	v_writelane_b32 v251, s5, 2
	v_writelane_b32 v251, s6, 3
	v_writelane_b32 v251, s7, 4
	v_writelane_b32 v251, s8, 5
	v_writelane_b32 v251, s9, 6
	v_writelane_b32 v251, s10, 7
	v_writelane_b32 v251, s11, 8
	v_writelane_b32 v251, s12, 9
	v_writelane_b32 v251, s13, 10
	v_writelane_b32 v251, s14, 11
	v_writelane_b32 v251, s15, 12
	v_writelane_b32 v251, s16, 13
	v_writelane_b32 v251, s17, 14
	v_writelane_b32 v251, s18, 15
	v_writelane_b32 v251, s19, 16
	v_writelane_b32 v251, s20, 17
	v_writelane_b32 v251, s21, 18
	v_writelane_b32 v251, s23, 20
	v_writelane_b32 v251, s24, 21
	v_writelane_b32 v251, s25, 22
	v_writelane_b32 v251, s26, 23
	v_writelane_b32 v251, s27, 24
	v_writelane_b32 v251, s28, 25
	v_writelane_b32 v251, s29, 26
	v_writelane_b32 v251, s30, 27
	v_writelane_b32 v251, s31, 28
	v_writelane_b32 v251, s32, 29
	v_writelane_b32 v251, s33, 30
	v_writelane_b32 v251, s34, 31
	v_writelane_b32 v251, s35, 32
	v_writelane_b32 v251, s36, 33
	v_writelane_b32 v251, s37, 34
	v_writelane_b32 v251, s38, 35
	v_writelane_b32 v251, s39, 36
	v_writelane_b32 v251, s40, 37
	v_writelane_b32 v251, s41, 38
	v_writelane_b32 v251, s42, 39
	v_writelane_b32 v251, s43, 40
	v_writelane_b32 v251, s44, 41
	v_writelane_b32 v251, s45, 42
	v_writelane_b32 v251, s46, 43
	v_writelane_b32 v251, s47, 44
	v_writelane_b32 v251, s48, 45
	v_writelane_b32 v251, s49, 46
	v_writelane_b32 v251, s50, 47
	v_writelane_b32 v251, s51, 48
	v_writelane_b32 v251, s52, 49
	v_writelane_b32 v251, s53, 50
	v_writelane_b32 v251, s54, 51
	v_writelane_b32 v251, s55, 52
	v_writelane_b32 v251, s56, 53
	v_writelane_b32 v251, s57, 54
	v_writelane_b32 v251, s58, 55
	v_writelane_b32 v251, s59, 56
	v_writelane_b32 v251, s60, 57
	v_writelane_b32 v251, s61, 58
	v_writelane_b32 v251, s62, 59
	v_writelane_b32 v251, s63, 60
	v_writelane_b32 v251, s64, 61
	v_writelane_b32 v251, s65, 62
	v_writelane_b32 v251, s66, 63
	v_writelane_b32 v252, s67, 0
	v_writelane_b32 v252, s68, 1
	v_writelane_b32 v252, s69, 2
	v_writelane_b32 v252, s70, 3
	v_writelane_b32 v252, s71, 4
	v_writelane_b32 v252, s72, 5
	v_writelane_b32 v252, s73, 6
	v_writelane_b32 v252, s74, 7
	v_writelane_b32 v252, s75, 8
	v_writelane_b32 v252, s76, 9
	v_writelane_b32 v252, s77, 10
	v_writelane_b32 v252, s78, 11
	v_writelane_b32 v252, s79, 12
	v_writelane_b32 v252, s80, 13
	v_writelane_b32 v252, s81, 14
	v_writelane_b32 v252, s82, 15
	v_writelane_b32 v252, s83, 16
	v_writelane_b32 v252, s84, 17
	v_writelane_b32 v252, s85, 18
	v_writelane_b32 v252, s86, 19
	v_writelane_b32 v252, s87, 20
	v_writelane_b32 v252, s88, 21
	v_writelane_b32 v252, s89, 22
	v_writelane_b32 v252, s90, 23
	v_writelane_b32 v252, s91, 24
	v_writelane_b32 v252, s92, 25
	v_writelane_b32 v252, s93, 26
	v_writelane_b32 v252, s94, 27
	v_writelane_b32 v252, s95, 28
	v_writelane_b32 v252, s96, 29
	v_writelane_b32 v252, s97, 30
	v_writelane_b32 v252, s98, 31
	v_writelane_b32 v252, s99, 32
	v_mov_b32_e32 v253, v1
	s_lshr_b32 s22, s1, 4
	s_lshl_b32 s22, s22, 3
	s_and_b32 s1, s1, 7
	s_or_b32 s1, s22, s1
	v_writelane_b32 v250, s1, 4
	s_mul_i32 s22, s0, 0x1000
	s_add_i32 s22, s22, 0x1e300
	v_writelane_b32 v250, s22, 1
	s_add_i32 s22, s22, 0x1000
	v_writelane_b32 v250, s22, 2
	s_add_i32 s22, s22, -1
	v_writelane_b32 v250, s22, 3
	s_mov_b32 s22, 1
	v_writelane_b32 v250, s22, 0
	s_branch .Lcv_entry
